# attention: V transpose reads issued at the start of the exp block (after the rescale decision) instead of right behind the QK MFMAs
# speedup vs baseline: 1.0024x; 1.0024x over previous
.LBB0_789:
	ds_read_b64_tr_b16 v[168:169], v35
	ds_read_b64_tr_b16 v[170:171], v35 offset:2560
	ds_read_b64_tr_b16 v[160:161], v35 offset:32
	ds_read_b64_tr_b16 v[162:163], v35 offset:2592
	ds_read_b64_tr_b16 v[176:177], v35 offset:64
	ds_read_b64_tr_b16 v[178:179], v35 offset:2624
	ds_read_b64_tr_b16 v[164:165], v35 offset:96
	ds_read_b64_tr_b16 v[166:167], v35 offset:2656
	v_exp_f32_e32 v37, v192
	v_exp_f32_e32 v38, v196
	v_exp_f32_e32 v39, v193
	v_exp_f32_e32 v196, v197
	v_exp_f32_e32 v193, v194
	v_exp_f32_e32 v194, v195
	v_cvt_pk_bf16_f32 v192, v37, v39
	v_exp_f32_e32 v37, v180
	v_exp_f32_e32 v39, v181
	v_cvt_pk_bf16_f32 v193, v193, v194
	v_cvt_pk_bf16_f32 v194, v38, v196
	v_exp_f32_e32 v38, v188
	v_exp_f32_e32 v188, v189
	v_exp_f32_e32 v181, v182
	v_exp_f32_e32 v182, v183
	v_exp_f32_e32 v197, v198
	v_exp_f32_e32 v195, v199
	v_cvt_pk_bf16_f32 v180, v37, v39
	v_cvt_pk_bf16_f32 v181, v181, v182
	v_cvt_pk_bf16_f32 v182, v38, v188
	v_exp_f32_e32 v37, v156
	v_exp_f32_e32 v38, v184
	v_exp_f32_e32 v39, v157
	v_exp_f32_e32 v184, v185
	v_exp_f32_e32 v157, v158
	v_exp_f32_e32 v158, v159
	s_mov_b32 s62, s60
	s_mov_b32 s63, s60
	v_cvt_pk_bf16_f32 v195, v197, v195
	s_mov_b32 s61, s60
	v_mov_b64_e32 v[198:199], s[62:63]
	v_mov_b64_e32 v[196:197], s[60:61]
	v_exp_f32_e32 v189, v190
	v_exp_f32_e32 v183, v191
	v_exp_f32_e32 v185, v186
	v_exp_f32_e32 v159, v187
	v_cvt_pk_bf16_f32 v156, v37, v39
	v_cvt_pk_bf16_f32 v157, v157, v158
	v_cvt_pk_bf16_f32 v158, v38, v184
	v_exp_f32_e32 v37, v152
	v_exp_f32_e32 v38, v172
	v_exp_f32_e32 v39, v153
	v_exp_f32_e32 v172, v173
	v_exp_f32_e32 v153, v154
	v_exp_f32_e32 v173, v174
	v_exp_f32_e32 v154, v155
	v_exp_f32_e32 v155, v175
	v_cvt_pk_bf16_f32 v183, v189, v183
	v_cvt_pk_bf16_f32 v159, v185, v159
	v_cvt_pk_bf16_f32 v152, v37, v39
	v_cvt_pk_bf16_f32 v153, v153, v154
	v_cvt_pk_bf16_f32 v154, v38, v172
	v_cvt_pk_bf16_f32 v155, v173, v155
	v_mfma_f32_16x16x32_bf16 v[116:119], v[196:199], v[192:195], v[116:119]
	v_subrev_u32_e32 v34, s73, v34
	v_add_u32_e32 v35, 0x1400, v35
	s_andn2_b64 vcc, exec, s[34:35]
	v_mfma_f32_16x16x32_bf16 v[64:67], v[196:199], v[180:183], v[64:67]
	v_mfma_f32_16x16x32_bf16 v[44:47], v[196:199], v[156:159], v[44:47]
	v_mfma_f32_16x16x32_bf16 v[16:19], v[196:199], v[152:155], v[16:19]
	s_waitcnt lgkmcnt(6)
	v_mfma_f32_16x16x32_bf16 v[96:99], v[168:171], v[192:195], v[96:99]
	v_mfma_f32_16x16x32_bf16 v[60:63], v[168:171], v[180:183], v[60:63]
	v_mfma_f32_16x16x32_bf16 v[40:43], v[168:171], v[156:159], v[40:43]
	v_mfma_f32_16x16x32_bf16 v[8:11], v[168:171], v[152:155], v[8:11]
	s_waitcnt lgkmcnt(4)
	v_mfma_f32_16x16x32_bf16 v[68:71], v[160:163], v[192:195], v[68:71]
	v_mfma_f32_16x16x32_bf16 v[48:51], v[160:163], v[180:183], v[48:51]
	v_mfma_f32_16x16x32_bf16 v[20:23], v[160:163], v[156:159], v[20:23]
	v_mfma_f32_16x16x32_bf16 v[0:3], v[160:163], v[152:155], v[0:3]
	s_waitcnt lgkmcnt(2)
	v_mfma_f32_16x16x32_bf16 v[92:95], v[176:179], v[192:195], v[92:95]
	v_mfma_f32_16x16x32_bf16 v[56:59], v[176:179], v[180:183], v[56:59]
	v_mfma_f32_16x16x32_bf16 v[28:31], v[176:179], v[156:159], v[28:31]
	v_mfma_f32_16x16x32_bf16 v[12:15], v[176:179], v[152:155], v[12:15]
	s_waitcnt lgkmcnt(0)
	v_mfma_f32_16x16x32_bf16 v[80:83], v[164:167], v[192:195], v[80:83]
	v_mfma_f32_16x16x32_bf16 v[52:55], v[164:167], v[180:183], v[52:55]
	v_mfma_f32_16x16x32_bf16 v[24:27], v[164:167], v[156:159], v[24:27]
	v_mfma_f32_16x16x32_bf16 v[4:7], v[164:167], v[152:155], v[4:7]
	s_cbranch_vccz .LBB0_801
.LBB0_790:
	s_waitcnt lgkmcnt(3)
	v_mfma_f32_16x16x32_bf16 v[152:155], v[144:147], v[72:75], v[228:231]
	s_waitcnt lgkmcnt(2)
	v_mfma_f32_16x16x32_bf16 v[192:195], v[148:151], v[76:79], v[152:155]
	v_mfma_f32_16x16x32_bf16 v[152:155], v[144:147], v[84:87], v[232:235]
	v_mfma_f32_16x16x32_bf16 v[180:183], v[148:151], v[88:91], v[152:155]
	s_mov_b32 s6, s53
	s_add_i32 s53, s53, 1
	s_cmp_ge_u32 s53, s52
	v_mfma_f32_16x16x32_bf16 v[152:155], v[144:147], v[100:103], v[248:251]
	s_cselect_b64 s[34:35], -1, 0
	s_cmp_lt_u32 s53, s52
	s_cselect_b32 s6, s53, s6
	v_mfma_f32_16x16x32_bf16 v[144:147], v[144:147], v[108:111], v[220:223]
	v_lshl_or_b32 v37, s6, 5, v201
	v_mad_u32_u24 v38, v37, s3, v32
	v_mfma_f32_16x16x32_bf16 v[156:159], v[148:151], v[104:107], v[152:155]
	v_mfma_f32_16x16x32_bf16 v[152:155], v[148:151], v[112:115], v[144:147]
	s_waitcnt lgkmcnt(1)
	v_mfma_f32_16x16x32_bf16 v[144:147], v[140:143], v[72:75], v[228:231]
	s_waitcnt lgkmcnt(0)
	v_mfma_f32_16x16x32_bf16 v[196:199], v[136:139], v[76:79], v[144:147]
	s_nop 0
	v_mfma_f32_16x16x32_bf16 v[144:147], v[140:143], v[84:87], v[232:235]
	v_mfma_f32_16x16x32_bf16 v[188:191], v[136:139], v[88:91], v[144:147]
	v_mfma_f32_16x16x32_bf16 v[144:147], v[140:143], v[100:103], v[248:251]
	v_mfma_f32_16x16x32_bf16 v[140:143], v[140:143], v[108:111], v[220:223]
	v_mfma_f32_16x16x32_bf16 v[184:187], v[136:139], v[104:107], v[144:147]
	s_nop 5
	ds_read_b128 v[144:147], v38
	ds_read_b128 v[148:151], v38 offset:64
	v_mfma_f32_16x16x32_bf16 v[172:175], v[136:139], v[112:115], v[140:143]
	s_nop 2
	ds_read_b128 v[140:143], v38 offset:2304
	ds_read_b128 v[136:139], v38 offset:2368
	s_andn2_b64 vcc, exec, s[86:87]
	s_cbranch_vccnz .LBB0_792
